# attention key loop: static s_setprio 1 for waves 4-7 (younger half), reset after the loop
# speedup vs baseline: 1.0071x; 1.0071x over previous
.LBB0_703:
	s_setprio 0
	v_mov_b32_e32 v32, v233
	s_nop 1
	v_permlane32_swap_b32_e32 v233, v32
	v_add_f32_e32 v32, v233, v32
	v_div_scale_f32 v33, s[8:9], v32, v32, 1.0
	v_rcp_f32_e32 v34, v33
	v_ashrrev_i32_e32 v205, 31, v204
	v_readlane_b32 s8, v252, 55
	v_readlane_b32 s9, v252, 56
	v_fma_f32 v35, -v33, v34, 1.0
	v_fmac_f32_e32 v34, v35, v34
	v_div_scale_f32 v35, vcc, 1.0, v32, 1.0
	v_mul_f32_e32 v36, v35, v34
	v_fma_f32 v37, -v33, v36, v35
	v_fmac_f32_e32 v36, v37, v34
	v_fma_f32 v33, -v33, v36, v35
	v_div_fmas_f32 v33, v33, v34, v36
	v_div_fixup_f32 v34, v33, v32, 1.0
	v_lshlrev_b64 v[32:33], 11, v[204:205]
	v_mul_f32_e32 v0, v0, v34
	v_mul_f32_e32 v1, v1, v34
	v_lshl_add_u64 v[32:33], s[8:9], 0, v[32:33]
	s_mov_b32 s7, s37
	v_cvt_pk_bf16_f32 v0, v0, v1
	v_mul_f32_e32 v1, v2, v34
	v_mul_f32_e32 v2, v3, v34
	v_lshl_add_u64 v[32:33], v[32:33], 0, s[6:7]
	v_lshlrev_b32_e32 v196, 1, v226
	v_cvt_pk_bf16_f32 v1, v1, v2
	v_mul_f32_e32 v2, v16, v34
	v_mul_f32_e32 v3, v17, v34
	v_lshl_add_u64 v[32:33], v[32:33], 0, v[196:197]
	v_cvt_pk_bf16_f32 v2, v2, v3
	v_mul_f32_e32 v3, v18, v34
	v_mul_f32_e32 v16, v19, v34
	v_cvt_pk_bf16_f32 v3, v3, v16
	global_store_dwordx2 v[32:33], v[0:1], off
	global_store_dwordx2 v[32:33], v[2:3], off offset:64
	v_mul_f32_e32 v0, v4, v34
	v_mul_f32_e32 v1, v5, v34
	v_cvt_pk_bf16_f32 v0, v0, v1
	v_mul_f32_e32 v1, v6, v34
	v_mul_f32_e32 v2, v7, v34
	v_cvt_pk_bf16_f32 v1, v1, v2
	v_mul_f32_e32 v2, v20, v34
	v_mul_f32_e32 v3, v21, v34
	v_cvt_pk_bf16_f32 v2, v2, v3
	v_mul_f32_e32 v3, v22, v34
	v_mul_f32_e32 v4, v23, v34
	v_cvt_pk_bf16_f32 v3, v3, v4
	global_store_dwordx2 v[32:33], v[0:1], off offset:16
	global_store_dwordx2 v[32:33], v[2:3], off offset:80
	v_mul_f32_e32 v0, v8, v34
	v_mul_f32_e32 v1, v9, v34
	v_cvt_pk_bf16_f32 v0, v0, v1
	v_mul_f32_e32 v1, v10, v34
	v_mul_f32_e32 v2, v11, v34
	v_cvt_pk_bf16_f32 v1, v1, v2
	v_mul_f32_e32 v2, v24, v34
	v_mul_f32_e32 v3, v25, v34
	v_cvt_pk_bf16_f32 v2, v2, v3
	v_mul_f32_e32 v3, v26, v34
	v_mul_f32_e32 v4, v27, v34
	v_cvt_pk_bf16_f32 v3, v3, v4
	global_store_dwordx2 v[32:33], v[0:1], off offset:32
	global_store_dwordx2 v[32:33], v[2:3], off offset:96
	v_mul_f32_e32 v0, v12, v34
	v_mul_f32_e32 v1, v13, v34
	v_readlane_b32 s12, v251, 1
	v_cvt_pk_bf16_f32 v0, v0, v1
	v_mul_f32_e32 v1, v14, v34
	v_mul_f32_e32 v2, v15, v34
	v_readlane_b32 s14, v251, 3
	v_cvt_pk_bf16_f32 v1, v1, v2
	v_mul_f32_e32 v2, v28, v34
	v_mul_f32_e32 v3, v29, v34
	s_add_i32 s3, s3, s14
	s_add_i32 s1, s1, s14
	v_cvt_pk_bf16_f32 v2, v2, v3
	v_mul_f32_e32 v3, v30, v34
	s_cmpk_gt_i32 s3, 0xff
	v_mul_f32_e32 v4, v31, v34
	v_cvt_pk_bf16_f32 v3, v3, v4
	global_store_dwordx2 v[32:33], v[0:1], off offset:48
	v_readlane_b32 s13, v251, 2
	v_readlane_b32 s15, v251, 4
	global_store_dwordx2 v[32:33], v[2:3], off offset:112
	s_cbranch_scc1 .LBB0_676

.LBB0_716:
	s_or_b64 exec, exec, s[8:9]
	s_waitcnt vmcnt(4)
	v_mul_u32_u24_e32 v0, 0xd0, v33
	v_add3_u32 v227, 0, v0, v196
	s_waitcnt lgkmcnt(0)
	s_barrier
	ds_read_b128 v[0:3], v227
	s_waitcnt vmcnt(1)
	ds_read_b128 v[4:7], v227 offset:32
	s_waitcnt vmcnt(0) lgkmcnt(1)
	v_mfma_f32_32x32x16_bf16 v[16:31], v[0:3], v[112:115], 0
	ds_read_b128 v[0:3], v227 offset:6656
	ds_read_b128 v[8:11], v227 offset:6688
	v_lshlrev_b32_e32 v228, 2, v32
	v_or_b32_e32 v229, s12, v33
	s_and_b32 s7, s1, 7
	s_lshl_b32 s36, s7, 7
	s_lshl_b32 s7, s11, 2
	s_mov_b32 s60, 0
	s_waitcnt lgkmcnt(1)
	v_mfma_f32_32x32x16_bf16 v[34:49], v[0:3], v[112:115], 0
	s_movk_i32 s8, 0xc0
	s_lshl_b32 s11, s2, 8
	s_mov_b32 s61, s60
	s_mov_b32 s62, s60
	s_mov_b32 s63, s60
	s_mov_b32 s64, s60
	s_mov_b32 s65, s60
	v_mfma_f32_32x32x16_bf16 v[16:31], v[4:7], v[116:119], v[16:31]
	ds_read_b128 v[0:3], v227 offset:64
	ds_read_b128 v[4:7], v227 offset:96
	s_mov_b32 s66, s60
	s_mov_b32 s67, s60
	s_mov_b32 s68, s60
	s_mov_b32 s69, s60
	s_mov_b32 s70, s60
	s_mov_b32 s71, s60
	s_waitcnt lgkmcnt(2)
	v_mfma_f32_32x32x16_bf16 v[34:49], v[8:11], v[116:119], v[34:49]
	s_mov_b32 s72, s60
	s_mov_b32 s73, s60
	s_mov_b32 s74, s60
	s_mov_b32 s75, s60
	v_mov_b32_e32 v138, v197
	v_mov_b32_e32 v139, v197
	v_mov_b32_e32 v136, v197
	s_waitcnt lgkmcnt(1)
	v_mfma_f32_32x32x16_bf16 v[16:31], v[0:3], v[120:123], v[16:31]
	ds_read_b128 v[0:3], v227 offset:6720
	ds_read_b128 v[8:11], v227 offset:6752
	v_mov_b32_e32 v137, v197
	v_mov_b64_e32 v[154:155], v[138:139]
	v_ashrrev_i32_e32 v205, 31, v204
	s_add_i32 s15, s7, 4
	v_add_u32_e32 v231, 0, v51
	v_lshlrev_b32_e32 v212, 2, v54
	s_waitcnt lgkmcnt(1)
	v_mfma_f32_32x32x16_bf16 v[34:49], v[0:3], v[120:123], v[34:49]
	ds_read_b128 v[0:3], v227 offset:128
	v_mov_b32_e32 v213, v197
	v_lshlrev_b32_e32 v214, 3, v52
	v_mov_b32_e32 v215, v197
	v_lshlrev_b32_e32 v216, 2, v52
	v_mov_b32_e32 v217, v197
	v_mul_hi_u32_u24_e32 v219, 6, v54
	v_mfma_f32_32x32x16_bf16 v[16:31], v[4:7], v[124:127], v[16:31]
	v_lshrrev_b32_e32 v4, 2, v50
	v_and_or_b32 v33, v4, 3, v228
	v_lshlrev_b32_e32 v4, 1, v50
	v_and_b32_e32 v53, 32, v4
	v_lshlrev_b32_e32 v4, 3, v50
	v_and_b32_e32 v55, 24, v4
	v_mul_u32_u24_e32 v218, 6, v54
	s_waitcnt lgkmcnt(1)
	v_mfma_f32_32x32x16_bf16 v[34:49], v[8:11], v[124:127], v[34:49]
	ds_read_b128 v[4:7], v227 offset:6784
	ds_read_b128 v[8:11], v227 offset:160
	ds_read_b128 v[58:61], v227 offset:6816
	v_mul_hi_u32_u24_e32 v221, 6, v52
	v_mul_u32_u24_e32 v220, 6, v52
	v_mov_b32_e32 v234, 0
	v_mov_b64_e32 v[152:153], v[136:137]
	s_waitcnt lgkmcnt(0)
	v_mfma_f32_32x32x16_bf16 v[16:31], v[0:3], v[128:131], v[16:31]
	s_barrier
	v_mfma_f32_32x32x16_bf16 v[34:49], v[4:7], v[128:131], v[34:49]
	v_mfma_f32_32x32x16_bf16 v[16:31], v[8:11], v[132:135], v[16:31]
	v_mov_b64_e32 v[0:1], s[60:61]
	v_mov_b64_e32 v[14:15], s[74:75]
	v_mov_b64_e32 v[2:3], s[62:63]
	v_mov_b64_e32 v[4:5], s[64:65]
	v_mov_b64_e32 v[6:7], s[66:67]
	v_mov_b64_e32 v[8:9], s[68:69]
	v_mov_b64_e32 v[10:11], s[70:71]
	v_mfma_f32_32x32x16_bf16 v[34:49], v[58:61], v[132:135], v[34:49]
	s_nop 3
	v_max_f32_e32 v32, v17, v17
	v_max_f32_e32 v62, v16, v16
	v_max_f32_e32 v32, v62, v32
	v_mov_b64_e32 v[12:13], s[72:73]
	s_nop 3
	v_max3_f32 v58, v18, v19, v35
	v_max3_f32 v32, v32, v34, v36
	v_max3_f32 v32, v32, v37, v20
	v_max3_f32 v58, v58, v22, v23
	v_max3_f32 v32, v32, v21, v38
	v_max3_f32 v58, v58, v40, v41
	v_max3_f32 v32, v32, v39, v24
	v_max3_f32 v58, v58, v26, v27
	v_max3_f32 v32, v32, v25, v42
	v_max3_f32 v58, v58, v44, v45
	v_max3_f32 v32, v32, v43, v28
	v_max3_f32 v58, v58, v30, v31
	v_max3_f32 v32, v32, v29, v46
	v_max3_f32 v58, v58, v48, v49
	v_max3_f32 v32, v32, v47, v58
	v_mov_b32_e32 v58, v32
	s_nop 1
	v_permlane32_swap_b32_e32 v32, v58
	v_max_f32_e32 v58, v58, v58
	v_max_f32_e32 v32, v32, v32
	v_max_f32_e32 v230, v32, v58
	v_sub_f32_e32 v66, v18, v230
	v_sub_f32_e32 v64, v16, v230
	v_mad_u32_u24 v16, v33, s8, 0
	s_add_i32 s8, s11, 0xffffc140
	v_and_b32_e32 v18, 7, v50
	v_sub_f32_e32 v65, v17, v230
	v_add3_u32 v232, v16, v53, v55
	v_or_b32_e32 v233, s8, v228
	v_lshl_add_u64 v[16:17], v[56:57], 0, s[36:37]
	v_lshlrev_b32_e32 v196, 4, v18
	v_readlane_b32 s8, v250, 20
	v_lshl_add_u64 v[16:17], v[16:17], 0, v[196:197]
	v_readlane_b32 s9, v250, 21
	v_xor_b32_e32 v32, 0x80000000, v230
	v_sub_f32_e32 v79, v31, v230
	v_sub_f32_e32 v78, v30, v230
	v_sub_f32_e32 v77, v29, v230
	v_sub_f32_e32 v76, v28, v230
	v_sub_f32_e32 v75, v27, v230
	v_sub_f32_e32 v74, v26, v230
	v_sub_f32_e32 v73, v25, v230
	v_sub_f32_e32 v72, v24, v230
	v_sub_f32_e32 v71, v23, v230
	v_sub_f32_e32 v70, v22, v230
	v_sub_f32_e32 v69, v21, v230
	v_sub_f32_e32 v68, v20, v230
	v_sub_f32_e32 v67, v19, v230
	v_lshl_add_u64 v[210:211], s[8:9], 0, v[16:17]
	v_mov_b64_e32 v[30:31], v[14:15]
	v_sub_f32_e32 v111, v49, v230
	v_sub_f32_e32 v110, v48, v230
	v_sub_f32_e32 v109, v47, v230
	v_sub_f32_e32 v108, v46, v230
	v_sub_f32_e32 v107, v45, v230
	v_sub_f32_e32 v106, v44, v230
	v_sub_f32_e32 v105, v43, v230
	v_sub_f32_e32 v104, v42, v230
	v_sub_f32_e32 v103, v41, v230
	v_sub_f32_e32 v102, v40, v230
	v_sub_f32_e32 v101, v39, v230
	v_sub_f32_e32 v100, v38, v230
	v_sub_f32_e32 v99, v37, v230
	v_sub_f32_e32 v98, v36, v230
	v_sub_f32_e32 v97, v35, v230
	v_sub_f32_e32 v96, v34, v230
	v_lshlrev_b32_e32 v196, 3, v54
	v_mov_b32_e32 v48, 0
	v_mov_b64_e32 v[28:29], v[12:13]
	v_mov_b64_e32 v[26:27], v[10:11]
	v_mov_b64_e32 v[24:25], v[8:9]
	v_mov_b64_e32 v[22:23], v[6:7]
	v_mov_b64_e32 v[20:21], v[4:5]
	v_mov_b64_e32 v[18:19], v[2:3]
	v_mov_b64_e32 v[16:17], v[0:1]
	v_mov_b32_e32 v33, v32
	v_mov_b32_e32 v34, v32
	v_mov_b32_e32 v35, v32
	v_mov_b32_e32 v36, v32
	v_mov_b32_e32 v37, v32
	v_mov_b32_e32 v38, v32
	v_mov_b32_e32 v39, v32
	v_mov_b32_e32 v40, v32
	v_mov_b32_e32 v41, v32
	v_mov_b32_e32 v42, v32
	v_mov_b32_e32 v43, v32
	v_mov_b32_e32 v44, v32
	v_mov_b32_e32 v45, v32
	v_mov_b32_e32 v46, v32
	v_mov_b32_e32 v47, v32
	v_readfirstlane_b32 s22, v199
	s_lshr_b32 s22, s22, 8
	s_cmp_eq_u32 s22, 1
	s_cbranch_scc0 .Lprio_skip_717
	s_setprio 1
.Lprio_skip_717:
.LBB0_717:
	s_add_i32 s22, s60, 3
	s_cmp_lt_u32 s22, s15
	s_cselect_b64 s[8:9], -1, 0
	s_cmp_ge_u32 s22, s15
	s_cbranch_scc1 .LBB0_721
	v_lshl_add_u64 v[50:51], v[206:207], 0, v[220:221]
	global_load_dwordx4 v[140:143], v[50:51], off
	s_and_saveexec_b64 s[12:13], s[42:43]
	s_cbranch_execz .LBB0_720
	v_lshl_add_u64 v[50:51], v[208:209], 0, v[218:219]
	global_load_dwordx4 v[136:139], v[50:51], off

.LBB0_748:
	s_setprio 0
	v_mov_b32_e32 v32, v234
	s_nop 1
	v_permlane32_swap_b32_e32 v234, v32
	v_add_f32_e32 v32, v234, v32
	v_div_scale_f32 v33, s[8:9], v32, v32, 1.0
	v_rcp_f32_e32 v34, v33
	v_readlane_b32 s8, v252, 55
	v_readlane_b32 s9, v252, 56
	s_mov_b32 s7, s37
	v_fma_f32 v35, -v33, v34, 1.0
	v_fmac_f32_e32 v34, v35, v34
	v_div_scale_f32 v35, vcc, 1.0, v32, 1.0
	v_mul_f32_e32 v36, v35, v34
	v_fma_f32 v37, -v33, v36, v35
	v_fmac_f32_e32 v36, v37, v34
	v_fma_f32 v33, -v33, v36, v35
	v_div_fmas_f32 v33, v33, v34, v36
	v_div_fixup_f32 v34, v33, v32, 1.0
	v_lshlrev_b64 v[32:33], 11, v[204:205]
	v_mul_f32_e32 v0, v0, v34
	v_mul_f32_e32 v1, v1, v34
	v_lshl_add_u64 v[32:33], s[8:9], 0, v[32:33]
	v_cvt_pk_bf16_f32 v0, v0, v1
	v_mul_f32_e32 v1, v2, v34
	v_mul_f32_e32 v2, v3, v34
	v_lshl_add_u64 v[32:33], v[32:33], 0, s[6:7]
	v_lshlrev_b32_e32 v196, 1, v228
	v_cvt_pk_bf16_f32 v1, v1, v2
	v_mul_f32_e32 v2, v16, v34
	v_mul_f32_e32 v3, v17, v34
	v_lshl_add_u64 v[32:33], v[32:33], 0, v[196:197]
	v_cvt_pk_bf16_f32 v2, v2, v3
	v_mul_f32_e32 v3, v18, v34
	v_mul_f32_e32 v16, v19, v34
	v_cvt_pk_bf16_f32 v3, v3, v16
	global_store_dwordx2 v[32:33], v[0:1], off
	global_store_dwordx2 v[32:33], v[2:3], off offset:64
	v_mul_f32_e32 v0, v4, v34
	v_mul_f32_e32 v1, v5, v34
	v_cvt_pk_bf16_f32 v0, v0, v1
	v_mul_f32_e32 v1, v6, v34
	v_mul_f32_e32 v2, v7, v34
	v_cvt_pk_bf16_f32 v1, v1, v2
	v_mul_f32_e32 v2, v20, v34
	v_mul_f32_e32 v3, v21, v34
	v_cvt_pk_bf16_f32 v2, v2, v3
	v_mul_f32_e32 v3, v22, v34
	v_mul_f32_e32 v4, v23, v34
	v_cvt_pk_bf16_f32 v3, v3, v4
	global_store_dwordx2 v[32:33], v[0:1], off offset:16
	global_store_dwordx2 v[32:33], v[2:3], off offset:80
	v_mul_f32_e32 v0, v8, v34
	v_mul_f32_e32 v1, v9, v34
	v_cvt_pk_bf16_f32 v0, v0, v1
	v_mul_f32_e32 v1, v10, v34
	v_mul_f32_e32 v2, v11, v34
	v_cvt_pk_bf16_f32 v1, v1, v2
	v_mul_f32_e32 v2, v24, v34
	v_mul_f32_e32 v3, v25, v34
	v_cvt_pk_bf16_f32 v2, v2, v3
	v_mul_f32_e32 v3, v26, v34
	v_mul_f32_e32 v4, v27, v34
	v_cvt_pk_bf16_f32 v3, v3, v4
	global_store_dwordx2 v[32:33], v[0:1], off offset:32
	global_store_dwordx2 v[32:33], v[2:3], off offset:96
	v_mul_f32_e32 v0, v12, v34
	v_mul_f32_e32 v1, v13, v34
	v_cvt_pk_bf16_f32 v0, v0, v1
	v_mul_f32_e32 v1, v14, v34
	v_mul_f32_e32 v2, v15, v34
	v_cvt_pk_bf16_f32 v1, v1, v2
	v_mul_f32_e32 v2, v28, v34
	v_mul_f32_e32 v3, v29, v34
	v_cvt_pk_bf16_f32 v2, v2, v3
	v_mul_f32_e32 v3, v30, v34
	v_mul_f32_e32 v4, v31, v34
	v_mov_b32_e32 v34, v199
	v_cvt_pk_bf16_f32 v3, v3, v4
	global_store_dwordx2 v[32:33], v[0:1], off offset:48
	global_store_dwordx2 v[32:33], v[2:3], off offset:112
	v_mov_b32_e32 v21, v197
	v_readfirstlane_b32 s8, v34
	s_ashr_i32 s12, s8, 1
	s_andn2_b32 s12, s12, 31
	v_and_b32_e32 v32, 31, v34
	s_add_i32 s8, s12, s11
	v_or_b32_e32 v204, s8, v32
	v_readlane_b32 s8, v251, 49
	v_readlane_b32 s9, v251, 50
	v_bfe_u32 v33, v34, 5, 1
	v_lshlrev_b32_e32 v20, 4, v33
	v_mov_b64_e32 v[0:1], s[8:9]
	v_mad_i64_i32 v[0:1], s[8:9], v204, s91, v[0:1]
	v_lshl_add_u64 v[2:3], v[0:1], 0, s[6:7]
	v_lshl_add_u64 v[2:3], v[2:3], 0, v[20:21]
	s_lshl_b32 s8, s14, 1
	s_mov_b32 s9, s37
	global_load_dwordx4 v[112:115], v[2:3], off
	global_load_dwordx4 v[116:119], v[2:3], off offset:32
	global_load_dwordx4 v[120:123], v[2:3], off offset:64
	global_load_dwordx4 v[124:127], v[2:3], off offset:96
	v_lshl_add_u64 v[0:1], v[0:1], 0, s[8:9]
	v_lshl_add_u64 v[0:1], v[0:1], 0, v[20:21]
	global_load_dwordx4 v[128:131], v[0:1], off offset:1024
	global_load_dwordx4 v[132:135], v[0:1], off offset:1056
	v_mul_hi_i32 v0, v34, s77
	v_lshrrev_b32_e32 v1, 31, v0
	v_ashrrev_i32_e32 v0, 1, v0
	v_add_u32_e32 v22, v0, v1
	v_mad_u64_u32 v[24:25], s[8:9], v22, -12, v[34:35]
	v_cmp_lt_i32_e32 vcc, 7, v24
	v_ashrrev_i32_e32 v23, 31, v22
	v_lshlrev_b32_e32 v0, 3, v24
	s_and_saveexec_b64 s[8:9], vcc
	s_xor_b64 s[8:9], exec, s[8:9]
	v_mov_b64_e32 v[2:3], s[82:83]
	v_mad_i64_i32 v[2:3], s[14:15], v22, s94, v[2:3]
	v_subrev_u32_e32 v196, 64, v0
	v_lshl_add_u64 v[0:1], v[196:197], 1, v[2:3]
	s_mov_b64 s[14:15], 0x500
	v_lshl_add_u64 v[206:207], v[0:1], 0, s[14:15]
	s_or_saveexec_b64 s[8:9], s[8:9]
	v_mov_b64_e32 v[36:37], 0x1c000
	s_xor_b64 exec, exec, s[8:9]
	s_cbranch_execz .LBB0_752
	v_readlane_b32 s14, v251, 43
	v_lshlrev_b64 v[2:3], 10, v[22:23]
	v_readlane_b32 s15, v251, 44
	s_mov_b32 s7, s37
	v_ashrrev_i32_e32 v1, 31, v0
	v_lshl_add_u64 v[2:3], s[14:15], 0, v[2:3]
	v_lshl_add_u64 v[2:3], v[2:3], 0, s[6:7]
	v_lshl_add_u64 v[206:207], v[0:1], 1, v[2:3]
	v_mov_b64_e32 v[36:37], 0x8000

.LBB0_762:
	s_nop 7
	v_max_f32_e32 v32, v1, v1
	v_max_f32_e32 v33, v0, v0
	v_max_f32_e32 v32, v33, v32
	v_max3_f32 v33, v2, v3, v17
	v_max3_f32 v32, v32, v16, v18
	v_max3_f32 v32, v32, v19, v4
	v_max3_f32 v33, v33, v6, v7
	v_max3_f32 v32, v32, v5, v20
	v_max3_f32 v33, v33, v22, v23
	v_max3_f32 v32, v32, v21, v8
	v_max3_f32 v33, v33, v10, v11
	v_max3_f32 v32, v32, v9, v24
	v_max3_f32 v33, v33, v26, v27
	v_max3_f32 v32, v32, v25, v12
	v_max3_f32 v33, v33, v14, v15
	v_max3_f32 v32, v32, v13, v28
	v_max3_f32 v33, v33, v30, v31
	v_max3_f32 v32, v32, v29, v33
	v_mov_b32_e32 v33, v32
	s_nop 1
	v_permlane32_swap_b32_e32 v32, v33
	s_cmp_lt_i32 s2, 0
	s_barrier
	s_cbranch_scc1 .LBB0_702
	v_lshrrev_b32_e32 v35, 2, v34
	v_max_f32_e32 v32, v32, v32
	v_max_f32_e32 v33, v33, v33
	v_and_or_b32 v35, v35, 3, v226
	v_lshlrev_b32_e32 v37, 1, v34
	v_lshlrev_b32_e32 v39, 3, v34
	v_max_f32_e32 v230, v32, v33
	s_movk_i32 s8, 0xc0
	v_and_b32_e32 v37, 32, v37
	v_and_b32_e32 v39, 24, v39
	v_sub_f32_e32 v64, v0, v230
	v_mad_u32_u24 v0, v35, s8, 0
	v_sub_f32_e32 v66, v2, v230
	v_add3_u32 v231, v0, v37, v39
	v_subrev_u32_e32 v0, s11, v226
	v_and_b32_e32 v2, 7, v34
	v_sub_f32_e32 v65, v1, v230
	v_add_u32_e32 v232, 0x60, v0
	v_lshl_add_u64 v[0:1], v[40:41], 0, s[36:37]
	v_lshlrev_b32_e32 v196, 4, v2
	v_readlane_b32 s8, v250, 20
	v_sub_f32_e32 v79, v15, v230
	v_sub_f32_e32 v78, v14, v230
	v_lshl_add_u64 v[0:1], v[0:1], 0, v[196:197]
	v_readlane_b32 s9, v250, 21
	v_mov_b32_e32 v14, v197
	v_mov_b32_e32 v15, v197
	v_mov_b32_e32 v138, v197
	v_mov_b32_e32 v139, v197
	s_lshl_b32 s2, s2, 2
	v_xor_b32_e32 v32, 0x80000000, v230
	v_sub_f32_e32 v111, v31, v230
	v_sub_f32_e32 v110, v30, v230
	v_sub_f32_e32 v109, v29, v230
	v_sub_f32_e32 v108, v28, v230
	v_sub_f32_e32 v107, v27, v230
	v_sub_f32_e32 v106, v26, v230
	v_sub_f32_e32 v105, v25, v230
	v_sub_f32_e32 v104, v24, v230
	v_sub_f32_e32 v103, v23, v230
	v_sub_f32_e32 v102, v22, v230
	v_sub_f32_e32 v101, v21, v230
	v_sub_f32_e32 v100, v20, v230
	v_sub_f32_e32 v99, v19, v230
	v_sub_f32_e32 v98, v18, v230
	v_sub_f32_e32 v97, v17, v230
	v_sub_f32_e32 v96, v16, v230
	v_sub_f32_e32 v77, v13, v230
	v_sub_f32_e32 v76, v12, v230
	v_sub_f32_e32 v75, v11, v230
	v_sub_f32_e32 v74, v10, v230
	v_sub_f32_e32 v73, v9, v230
	v_sub_f32_e32 v72, v8, v230
	v_sub_f32_e32 v71, v7, v230
	v_sub_f32_e32 v70, v6, v230
	v_sub_f32_e32 v69, v5, v230
	v_sub_f32_e32 v68, v4, v230
	v_sub_f32_e32 v67, v3, v230
	v_lshl_add_u64 v[210:211], s[8:9], 0, v[0:1]
	v_mov_b32_e32 v0, v197
	v_mov_b32_e32 v1, v197
	v_mov_b32_e32 v2, v197
	v_mov_b32_e32 v3, v197
	v_mov_b32_e32 v4, v197
	v_mov_b32_e32 v5, v197
	v_mov_b32_e32 v6, v197
	v_mov_b32_e32 v7, v197
	v_mov_b32_e32 v8, v197
	v_mov_b32_e32 v9, v197
	v_mov_b32_e32 v10, v197
	v_mov_b32_e32 v11, v197
	v_mov_b32_e32 v12, v197
	v_mov_b32_e32 v13, v197
	v_mov_b32_e32 v136, v197
	v_mov_b32_e32 v137, v197
	v_mov_b64_e32 v[154:155], v[138:139]
	v_mov_b64_e32 v[30:31], v[14:15]
	s_add_i32 s7, s2, 4
	v_lshlrev_b32_e32 v196, 3, v38
	v_lshlrev_b32_e32 v212, 2, v38
	v_mov_b32_e32 v213, v197
	v_lshlrev_b32_e32 v214, 3, v36
	v_mov_b32_e32 v215, v197
	v_lshlrev_b32_e32 v216, 2, v36
	v_mov_b32_e32 v217, v197
	v_mul_hi_u32_u24_e32 v219, 6, v38
	v_mul_u32_u24_e32 v218, 6, v38
	v_mul_hi_u32_u24_e32 v221, 6, v36
	v_mul_u32_u24_e32 v220, 6, v36
	s_mov_b32 s15, 0
	v_mov_b32_e32 v233, 0
	v_mov_b64_e32 v[152:153], v[136:137]
	v_mov_b32_e32 v48, 0
	v_mov_b64_e32 v[28:29], v[12:13]
	v_mov_b64_e32 v[26:27], v[10:11]
	v_mov_b64_e32 v[24:25], v[8:9]
	v_mov_b64_e32 v[22:23], v[6:7]
	v_mov_b64_e32 v[20:21], v[4:5]
	v_mov_b64_e32 v[18:19], v[2:3]
	v_mov_b64_e32 v[16:17], v[0:1]
	v_mov_b32_e32 v33, v32
	v_mov_b32_e32 v34, v32
	v_mov_b32_e32 v35, v32
	v_mov_b32_e32 v36, v32
	v_mov_b32_e32 v37, v32
	v_mov_b32_e32 v38, v32
	v_mov_b32_e32 v39, v32
	v_mov_b32_e32 v40, v32
	v_mov_b32_e32 v41, v32
	v_mov_b32_e32 v42, v32
	v_mov_b32_e32 v43, v32
	v_mov_b32_e32 v44, v32
	v_mov_b32_e32 v45, v32
	v_mov_b32_e32 v46, v32
	v_mov_b32_e32 v47, v32
	v_readfirstlane_b32 s22, v199
	s_lshr_b32 s22, s22, 8
	s_cmp_eq_u32 s22, 1
	s_cbranch_scc0 .Lprio_skip_764
	s_setprio 1
.Lprio_skip_764:
.LBB0_764:
	s_add_i32 s14, s15, 3
	s_cmp_lt_i32 s14, s7
	s_cselect_b64 s[8:9], -1, 0
	s_cmp_ge_i32 s14, s7
	s_cbranch_scc1 .LBB0_768
	v_lshl_add_u64 v[50:51], v[206:207], 0, v[220:221]
	global_load_dwordx4 v[140:143], v[50:51], off
	s_and_saveexec_b64 s[12:13], s[42:43]
	s_cbranch_execz .LBB0_767
	v_lshl_add_u64 v[50:51], v[208:209], 0, v[218:219]
	global_load_dwordx4 v[136:139], v[50:51], off
